# v40: gate epilogue issues the next row group's branch-tile loads right after the combine, before the pack and store of the current group
# baseline (speedup 1.0000x reference)
; __device__ __forceinline__ float lo2f(unsigned w) { return __uint_as_float(w << 16); }
; __device__ __forceinline__ float hi2f(unsigned w) { return __uint_as_float(w & 0xffff0000u); }
; __device__ __forceinline__ float sigm(float x) { return __builtin_amdgcn_rcpf(1.f + __expf(-x)); }
;   __device__ __forceinline__ void operator()(const f32x4 (&acc)[2][2][4][2], const Unit& u, int wr, int wc, int fr, int fq) const {
;     ...
;       const int q = s - 4, bjq = q >> 1, nq = q & 1;
; #pragma unroll
;       for (int ai = 0; ai < 2; ++ai)
; #pragma unroll
;         for (int m = 0; m < 4; ++m) {
;           float o[4] = {0.f, 0.f, 0.f, 0.f};
; #pragma unroll
;           for (int bj = 0; bj < 2; ++bj)
; #pragma unroll
;             for (int n = 0; n < 2; ++n) {
;               const int ib = 2 * bj + n;
;               const uint2 b2 = *(reinterpret_cast<const uint2*>(brs + (size_t)(ib * 16 + (ai * 2 + bjq) * 4 + m) * 512 + tid) + nq);
;               const f32x4 g = acc[ai][bj][m][n];
;               o[0] += sigm(g[0]) * lo2f(b2.x); o[1] += sigm(g[1]) * hi2f(b2.x);
;               o[2] += sigm(g[2]) * lo2f(b2.y); o[3] += sigm(g[3]) * hi2f(b2.y);
;             }
;           const int r = u.pm * 256 + ai * 128 + wr * 64 + m * 16 + fr;
;           const int d = dq * 256 + 64 * q + 16 * wc + 4 * fq;
;           uint2 w; w.x = pack2(o[0], o[1]); w.y = pack2(o[2], o[3]);
;           *reinterpret_cast<uint2*>(ACC + (size_t)r * 1024 + d) = w;
;         }
.LBB0_1416:
	s_mov_b32 s100, 0xbfb8aa3b
	s_add_i32 s15, s11, -4
	s_and_b32 s19, s2, 1
	s_lshl_b32 s2, s2, 5
	s_and_b32 s2, s2, 0xffffff00
	s_lshl_b32 s18, s15, 1
	s_lshl_b32 s15, s15, 6
	s_add_i32 s15, s15, s2
	s_and_b32 s14, s18, 0x7ffffffc
	s_lshl_b32 s2, s19, 3
	s_lshl_b32 s14, s14, 13
	s_add_i32 s2, s2, s14
	v_lshlrev_b32_e32 v144, 4, v140
	v_add_u32_e32 v144, s2, v144
	v_mov_b32_e32 v170, v144
	global_load_dwordx2 v[146:147], v170, s[48:49]
	v_add_u32_e32 v171, 0x20000, v144
	global_load_dwordx2 v[148:149], v171, s[48:49]
	v_add_u32_e32 v172, 0x40000, v144
	global_load_dwordx2 v[150:151], v172, s[48:49]
	v_add_u32_e32 v173, 0x60000, v144
	global_load_dwordx2 v[152:153], v173, s[48:49]
	v_add_u32_e32 v170, 0x2000, v144
	global_load_dwordx2 v[154:155], v170, s[48:49]
	v_add_u32_e32 v171, 0x22000, v144
	global_load_dwordx2 v[156:157], v171, s[48:49]
	v_add_u32_e32 v172, 0x42000, v144
	global_load_dwordx2 v[158:159], v172, s[48:49]
	v_add_u32_e32 v173, 0x62000, v144
	global_load_dwordx2 v[160:161], v173, s[48:49]
	v_add_u32_e32 v170, 0x4000, v144
	global_load_dwordx2 v[162:163], v170, s[48:49]
	v_add_u32_e32 v171, 0x24000, v144
	global_load_dwordx2 v[164:165], v171, s[48:49]
	v_add_u32_e32 v172, 0x44000, v144
	global_load_dwordx2 v[166:167], v172, s[48:49]
	v_add_u32_e32 v173, 0x64000, v144
	global_load_dwordx2 v[168:169], v173, s[48:49]
	v_or_b32_e32 v145, s15, v200
	v_lshl_add_u32 v143, s16, 8, v1
	v_lshlrev_b32_e32 v145, 1, v145
	v_lshl_add_u32 v145, v143, 11, v145
	v_pk_mul_f32 v[174:175], v[126:127], s[100:101] op_sel_hi:[1,0]
	v_pk_mul_f32 v[182:183], v[128:129], s[100:101] op_sel_hi:[1,0]
	v_exp_f32_e32 v174, v174
	v_exp_f32_e32 v175, v175
	v_exp_f32_e32 v182, v182
	v_exp_f32_e32 v183, v183
	v_pk_add_f32 v[174:175], v[174:175], 1.0 op_sel_hi:[1,0]
	v_pk_add_f32 v[182:183], v[182:183], 1.0 op_sel_hi:[1,0]
	v_rcp_f32_e32 v202, v174
	v_rcp_f32_e32 v203, v175
	v_rcp_f32_e32 v204, v182
	v_rcp_f32_e32 v205, v183
	v_pk_mul_f32 v[174:175], v[122:123], s[100:101] op_sel_hi:[1,0]
	v_pk_mul_f32 v[182:183], v[124:125], s[100:101] op_sel_hi:[1,0]
	v_exp_f32_e32 v174, v174
	v_exp_f32_e32 v175, v175
	v_exp_f32_e32 v182, v182
	v_exp_f32_e32 v183, v183
	v_pk_add_f32 v[174:175], v[174:175], 1.0 op_sel_hi:[1,0]
	v_pk_add_f32 v[182:183], v[182:183], 1.0 op_sel_hi:[1,0]
	v_rcp_f32_e32 v206, v174
	v_rcp_f32_e32 v207, v175
	v_rcp_f32_e32 v208, v182
	v_rcp_f32_e32 v209, v183
	v_pk_mul_f32 v[174:175], v[94:95], s[100:101] op_sel_hi:[1,0]
	v_pk_mul_f32 v[182:183], v[96:97], s[100:101] op_sel_hi:[1,0]
	v_exp_f32_e32 v174, v174
	v_exp_f32_e32 v175, v175
	v_exp_f32_e32 v182, v182
	v_exp_f32_e32 v183, v183
	v_pk_add_f32 v[174:175], v[174:175], 1.0 op_sel_hi:[1,0]
	v_pk_add_f32 v[182:183], v[182:183], 1.0 op_sel_hi:[1,0]
	v_rcp_f32_e32 v210, v174
	v_rcp_f32_e32 v211, v175
	v_rcp_f32_e32 v212, v182
	v_rcp_f32_e32 v213, v183
	v_pk_mul_f32 v[174:175], v[90:91], s[100:101] op_sel_hi:[1,0]
	v_pk_mul_f32 v[182:183], v[92:93], s[100:101] op_sel_hi:[1,0]
	v_exp_f32_e32 v174, v174
	v_exp_f32_e32 v175, v175
	v_exp_f32_e32 v182, v182
	v_exp_f32_e32 v183, v183
	v_pk_add_f32 v[174:175], v[174:175], 1.0 op_sel_hi:[1,0]
	v_pk_add_f32 v[182:183], v[182:183], 1.0 op_sel_hi:[1,0]
	v_rcp_f32_e32 v214, v174
	v_rcp_f32_e32 v215, v175
	v_rcp_f32_e32 v216, v182
	v_rcp_f32_e32 v217, v183
	s_waitcnt vmcnt(8)
	v_lshlrev_b32_e32 v218, 16, v146
	v_and_b32_e32 v219, 0xffff0000, v146
	v_lshlrev_b32_e32 v220, 16, v147
	v_and_b32_e32 v221, 0xffff0000, v147
	v_pk_fma_f32 v[222:223], v[202:203], v[218:219], 0 op_sel_hi:[1,1,0]
	v_pk_fma_f32 v[224:225], v[204:205], v[220:221], 0 op_sel_hi:[1,1,0]
	v_lshlrev_b32_e32 v218, 16, v148
	v_and_b32_e32 v219, 0xffff0000, v148
	v_lshlrev_b32_e32 v220, 16, v149
	v_and_b32_e32 v221, 0xffff0000, v149
	v_pk_fma_f32 v[222:223], v[206:207], v[218:219], v[222:223]
	v_pk_fma_f32 v[224:225], v[208:209], v[220:221], v[224:225]
	v_lshlrev_b32_e32 v218, 16, v150
	v_and_b32_e32 v219, 0xffff0000, v150
	v_lshlrev_b32_e32 v220, 16, v151
	v_and_b32_e32 v221, 0xffff0000, v151
	v_pk_fma_f32 v[222:223], v[210:211], v[218:219], v[222:223]
	v_pk_fma_f32 v[224:225], v[212:213], v[220:221], v[224:225]
	v_lshlrev_b32_e32 v218, 16, v152
	v_and_b32_e32 v219, 0xffff0000, v152
	v_lshlrev_b32_e32 v220, 16, v153
	v_and_b32_e32 v221, 0xffff0000, v153
	v_pk_fma_f32 v[222:223], v[214:215], v[218:219], v[222:223]
	v_pk_fma_f32 v[224:225], v[216:217], v[220:221], v[224:225]
	v_add_u32_e32 v170, 0x6000, v144
	global_load_dwordx2 v[146:147], v170, s[48:49]
	v_add_u32_e32 v171, 0x26000, v144
	global_load_dwordx2 v[148:149], v171, s[48:49]
	v_add_u32_e32 v172, 0x46000, v144
	global_load_dwordx2 v[150:151], v172, s[48:49]
	v_add_u32_e32 v173, 0x66000, v144
	global_load_dwordx2 v[152:153], v173, s[48:49]
	v_mov_b32_e32 v230, v145
	v_cvt_pk_bf16_f32 v226, v222, v223
	v_cvt_pk_bf16_f32 v227, v224, v225
	global_store_dwordx2 v230, v[226:227], s[84:85]
	v_pk_mul_f32 v[174:175], v[118:119], s[100:101] op_sel_hi:[1,0]
	v_pk_mul_f32 v[182:183], v[120:121], s[100:101] op_sel_hi:[1,0]
	v_exp_f32_e32 v174, v174
	v_exp_f32_e32 v175, v175
	v_exp_f32_e32 v182, v182
	v_exp_f32_e32 v183, v183
	v_pk_add_f32 v[174:175], v[174:175], 1.0 op_sel_hi:[1,0]
	v_pk_add_f32 v[182:183], v[182:183], 1.0 op_sel_hi:[1,0]
	v_rcp_f32_e32 v202, v174
	v_rcp_f32_e32 v203, v175
	v_rcp_f32_e32 v204, v182
	v_rcp_f32_e32 v205, v183
	v_pk_mul_f32 v[174:175], v[114:115], s[100:101] op_sel_hi:[1,0]
	v_pk_mul_f32 v[182:183], v[116:117], s[100:101] op_sel_hi:[1,0]
	v_exp_f32_e32 v174, v174
	v_exp_f32_e32 v175, v175
	v_exp_f32_e32 v182, v182
	v_exp_f32_e32 v183, v183
	v_pk_add_f32 v[174:175], v[174:175], 1.0 op_sel_hi:[1,0]
	v_pk_add_f32 v[182:183], v[182:183], 1.0 op_sel_hi:[1,0]
	v_rcp_f32_e32 v206, v174
	v_rcp_f32_e32 v207, v175
	v_rcp_f32_e32 v208, v182
	v_rcp_f32_e32 v209, v183
	v_pk_mul_f32 v[174:175], v[86:87], s[100:101] op_sel_hi:[1,0]
	v_pk_mul_f32 v[182:183], v[88:89], s[100:101] op_sel_hi:[1,0]
	v_exp_f32_e32 v174, v174
	v_exp_f32_e32 v175, v175
	v_exp_f32_e32 v182, v182
	v_exp_f32_e32 v183, v183
	v_pk_add_f32 v[174:175], v[174:175], 1.0 op_sel_hi:[1,0]
	v_pk_add_f32 v[182:183], v[182:183], 1.0 op_sel_hi:[1,0]
	v_rcp_f32_e32 v210, v174
	v_rcp_f32_e32 v211, v175
	v_rcp_f32_e32 v212, v182
	v_rcp_f32_e32 v213, v183
	v_pk_mul_f32 v[174:175], v[82:83], s[100:101] op_sel_hi:[1,0]
	v_pk_mul_f32 v[182:183], v[84:85], s[100:101] op_sel_hi:[1,0]
	v_exp_f32_e32 v174, v174
	v_exp_f32_e32 v175, v175
	v_exp_f32_e32 v182, v182
	v_exp_f32_e32 v183, v183
	v_pk_add_f32 v[174:175], v[174:175], 1.0 op_sel_hi:[1,0]
	v_pk_add_f32 v[182:183], v[182:183], 1.0 op_sel_hi:[1,0]
	v_rcp_f32_e32 v214, v174
	v_rcp_f32_e32 v215, v175
	v_rcp_f32_e32 v216, v182
	v_rcp_f32_e32 v217, v183
	s_waitcnt vmcnt(9)
; __device__ __forceinline__ float lo2f(unsigned w) { return __uint_as_float(w << 16); }
; __device__ __forceinline__ float hi2f(unsigned w) { return __uint_as_float(w & 0xffff0000u); }
; __device__ __forceinline__ float sigm(float x) { return __builtin_amdgcn_rcpf(1.f + __expf(-x)); }
;   __device__ __forceinline__ void operator()(const f32x4 (&acc)[2][2][4][2], const Unit& u, int wr, int wc, int fr, int fq) const {
;     ...
;       const int q = s - 4, bjq = q >> 1, nq = q & 1;
; #pragma unroll
;       for (int ai = 0; ai < 2; ++ai)
; #pragma unroll
;         for (int m = 0; m < 4; ++m) {
;           float o[4] = {0.f, 0.f, 0.f, 0.f};
; #pragma unroll
;           for (int bj = 0; bj < 2; ++bj)
; #pragma unroll
;             for (int n = 0; n < 2; ++n) {
;               const int ib = 2 * bj + n;
;               const uint2 b2 = *(reinterpret_cast<const uint2*>(brs + (size_t)(ib * 16 + (ai * 2 + bjq) * 4 + m) * 512 + tid) + nq);
;               const f32x4 g = acc[ai][bj][m][n];
;               o[0] += sigm(g[0]) * lo2f(b2.x); o[1] += sigm(g[1]) * hi2f(b2.x);
;               o[2] += sigm(g[2]) * lo2f(b2.y); o[3] += sigm(g[3]) * hi2f(b2.y);
;             }
;           const int r = u.pm * 256 + ai * 128 + wr * 64 + m * 16 + fr;
;           const int d = dq * 256 + 64 * q + 16 * wc + 4 * fq;
;           uint2 w; w.x = pack2(o[0], o[1]); w.y = pack2(o[2], o[3]);
;           *reinterpret_cast<uint2*>(ACC + (size_t)r * 1024 + d) = w;
;         }
	v_lshlrev_b32_e32 v218, 16, v154
	v_and_b32_e32 v219, 0xffff0000, v154
	v_lshlrev_b32_e32 v220, 16, v155
	v_and_b32_e32 v221, 0xffff0000, v155
	v_pk_fma_f32 v[222:223], v[202:203], v[218:219], 0 op_sel_hi:[1,1,0]
	v_pk_fma_f32 v[224:225], v[204:205], v[220:221], 0 op_sel_hi:[1,1,0]
	v_lshlrev_b32_e32 v218, 16, v156
	v_and_b32_e32 v219, 0xffff0000, v156
	v_lshlrev_b32_e32 v220, 16, v157
	v_and_b32_e32 v221, 0xffff0000, v157
	v_pk_fma_f32 v[222:223], v[206:207], v[218:219], v[222:223]
	v_pk_fma_f32 v[224:225], v[208:209], v[220:221], v[224:225]
	v_lshlrev_b32_e32 v218, 16, v158
	v_and_b32_e32 v219, 0xffff0000, v158
	v_lshlrev_b32_e32 v220, 16, v159
	v_and_b32_e32 v221, 0xffff0000, v159
	v_pk_fma_f32 v[222:223], v[210:211], v[218:219], v[222:223]
	v_pk_fma_f32 v[224:225], v[212:213], v[220:221], v[224:225]
	v_lshlrev_b32_e32 v218, 16, v160
	v_and_b32_e32 v219, 0xffff0000, v160
	v_lshlrev_b32_e32 v220, 16, v161
	v_and_b32_e32 v221, 0xffff0000, v161
	v_pk_fma_f32 v[222:223], v[214:215], v[218:219], v[222:223]
	v_pk_fma_f32 v[224:225], v[216:217], v[220:221], v[224:225]
	v_add_u32_e32 v170, 0x10000, v144
	global_load_dwordx2 v[154:155], v170, s[48:49]
	v_add_u32_e32 v171, 0x30000, v144
	global_load_dwordx2 v[156:157], v171, s[48:49]
	v_add_u32_e32 v172, 0x50000, v144
	global_load_dwordx2 v[158:159], v172, s[48:49]
	v_add_u32_e32 v173, 0x70000, v144
	global_load_dwordx2 v[160:161], v173, s[48:49]
	v_add_u32_e32 v231, 0x8000, v145
	v_cvt_pk_bf16_f32 v228, v222, v223
	v_cvt_pk_bf16_f32 v229, v224, v225
	global_store_dwordx2 v231, v[228:229], s[84:85]
	v_pk_mul_f32 v[174:175], v[110:111], s[100:101] op_sel_hi:[1,0]
	v_pk_mul_f32 v[182:183], v[112:113], s[100:101] op_sel_hi:[1,0]
	v_exp_f32_e32 v174, v174
	v_exp_f32_e32 v175, v175
	v_exp_f32_e32 v182, v182
	v_exp_f32_e32 v183, v183
	v_pk_add_f32 v[174:175], v[174:175], 1.0 op_sel_hi:[1,0]
	v_pk_add_f32 v[182:183], v[182:183], 1.0 op_sel_hi:[1,0]
	v_rcp_f32_e32 v202, v174
	v_rcp_f32_e32 v203, v175
	v_rcp_f32_e32 v204, v182
	v_rcp_f32_e32 v205, v183
	v_pk_mul_f32 v[174:175], v[106:107], s[100:101] op_sel_hi:[1,0]
	v_pk_mul_f32 v[182:183], v[108:109], s[100:101] op_sel_hi:[1,0]
	v_exp_f32_e32 v174, v174
	v_exp_f32_e32 v175, v175
	v_exp_f32_e32 v182, v182
	v_exp_f32_e32 v183, v183
	v_pk_add_f32 v[174:175], v[174:175], 1.0 op_sel_hi:[1,0]
	v_pk_add_f32 v[182:183], v[182:183], 1.0 op_sel_hi:[1,0]
	v_rcp_f32_e32 v206, v174
	v_rcp_f32_e32 v207, v175
	v_rcp_f32_e32 v208, v182
	v_rcp_f32_e32 v209, v183
	v_pk_mul_f32 v[174:175], v[78:79], s[100:101] op_sel_hi:[1,0]
	v_pk_mul_f32 v[182:183], v[80:81], s[100:101] op_sel_hi:[1,0]
	v_exp_f32_e32 v174, v174
	v_exp_f32_e32 v175, v175
	v_exp_f32_e32 v182, v182
	v_exp_f32_e32 v183, v183
	v_pk_add_f32 v[174:175], v[174:175], 1.0 op_sel_hi:[1,0]
	v_pk_add_f32 v[182:183], v[182:183], 1.0 op_sel_hi:[1,0]
	v_rcp_f32_e32 v210, v174
	v_rcp_f32_e32 v211, v175
	v_rcp_f32_e32 v212, v182
	v_rcp_f32_e32 v213, v183
	v_pk_mul_f32 v[174:175], v[74:75], s[100:101] op_sel_hi:[1,0]
	v_pk_mul_f32 v[182:183], v[76:77], s[100:101] op_sel_hi:[1,0]
	v_exp_f32_e32 v174, v174
	v_exp_f32_e32 v175, v175
	v_exp_f32_e32 v182, v182
	v_exp_f32_e32 v183, v183
	v_pk_add_f32 v[174:175], v[174:175], 1.0 op_sel_hi:[1,0]
	v_pk_add_f32 v[182:183], v[182:183], 1.0 op_sel_hi:[1,0]
	v_rcp_f32_e32 v214, v174
	v_rcp_f32_e32 v215, v175
	v_rcp_f32_e32 v216, v182
	v_rcp_f32_e32 v217, v183
	s_waitcnt vmcnt(10)
	v_lshlrev_b32_e32 v218, 16, v162
	v_and_b32_e32 v219, 0xffff0000, v162
	v_lshlrev_b32_e32 v220, 16, v163
	v_and_b32_e32 v221, 0xffff0000, v163
	v_pk_fma_f32 v[222:223], v[202:203], v[218:219], 0 op_sel_hi:[1,1,0]
	v_pk_fma_f32 v[224:225], v[204:205], v[220:221], 0 op_sel_hi:[1,1,0]
	v_lshlrev_b32_e32 v218, 16, v164
	v_and_b32_e32 v219, 0xffff0000, v164
	v_lshlrev_b32_e32 v220, 16, v165
	v_and_b32_e32 v221, 0xffff0000, v165
	v_pk_fma_f32 v[222:223], v[206:207], v[218:219], v[222:223]
	v_pk_fma_f32 v[224:225], v[208:209], v[220:221], v[224:225]
	v_lshlrev_b32_e32 v218, 16, v166
	v_and_b32_e32 v219, 0xffff0000, v166
	v_lshlrev_b32_e32 v220, 16, v167
	v_and_b32_e32 v221, 0xffff0000, v167
	v_pk_fma_f32 v[222:223], v[210:211], v[218:219], v[222:223]
	v_pk_fma_f32 v[224:225], v[212:213], v[220:221], v[224:225]
	v_lshlrev_b32_e32 v218, 16, v168
	v_and_b32_e32 v219, 0xffff0000, v168
	v_lshlrev_b32_e32 v220, 16, v169
	v_and_b32_e32 v221, 0xffff0000, v169
	v_pk_fma_f32 v[222:223], v[214:215], v[218:219], v[222:223]
	v_pk_fma_f32 v[224:225], v[216:217], v[220:221], v[224:225]
	v_add_u32_e32 v170, 0x12000, v144
	global_load_dwordx2 v[162:163], v170, s[48:49]
	v_add_u32_e32 v171, 0x32000, v144
	global_load_dwordx2 v[164:165], v171, s[48:49]
	v_add_u32_e32 v172, 0x52000, v144
	global_load_dwordx2 v[166:167], v172, s[48:49]
	v_add_u32_e32 v173, 0x72000, v144
	global_load_dwordx2 v[168:169], v173, s[48:49]
	v_add_u32_e32 v230, 0x10000, v145
	v_cvt_pk_bf16_f32 v226, v222, v223
	v_cvt_pk_bf16_f32 v227, v224, v225
	global_store_dwordx2 v230, v[226:227], s[84:85]
	v_pk_mul_f32 v[174:175], v[102:103], s[100:101] op_sel_hi:[1,0]
	v_pk_mul_f32 v[182:183], v[104:105], s[100:101] op_sel_hi:[1,0]
	v_exp_f32_e32 v174, v174
	v_exp_f32_e32 v175, v175
	v_exp_f32_e32 v182, v182
	v_exp_f32_e32 v183, v183
	v_pk_add_f32 v[174:175], v[174:175], 1.0 op_sel_hi:[1,0]
	v_pk_add_f32 v[182:183], v[182:183], 1.0 op_sel_hi:[1,0]
	v_rcp_f32_e32 v202, v174
	v_rcp_f32_e32 v203, v175
	v_rcp_f32_e32 v204, v182
	v_rcp_f32_e32 v205, v183
	v_pk_mul_f32 v[174:175], v[98:99], s[100:101] op_sel_hi:[1,0]
	v_pk_mul_f32 v[182:183], v[100:101], s[100:101] op_sel_hi:[1,0]
	v_exp_f32_e32 v174, v174
	v_exp_f32_e32 v175, v175
	v_exp_f32_e32 v182, v182
	v_exp_f32_e32 v183, v183
	v_pk_add_f32 v[174:175], v[174:175], 1.0 op_sel_hi:[1,0]
	v_pk_add_f32 v[182:183], v[182:183], 1.0 op_sel_hi:[1,0]
	v_rcp_f32_e32 v206, v174
	v_rcp_f32_e32 v207, v175
	v_rcp_f32_e32 v208, v182
	v_rcp_f32_e32 v209, v183
	v_pk_mul_f32 v[174:175], v[70:71], s[100:101] op_sel_hi:[1,0]
	v_pk_mul_f32 v[182:183], v[72:73], s[100:101] op_sel_hi:[1,0]
	v_exp_f32_e32 v174, v174
	v_exp_f32_e32 v175, v175
	v_exp_f32_e32 v182, v182
	v_exp_f32_e32 v183, v183
	v_pk_add_f32 v[174:175], v[174:175], 1.0 op_sel_hi:[1,0]
	v_pk_add_f32 v[182:183], v[182:183], 1.0 op_sel_hi:[1,0]
	v_rcp_f32_e32 v210, v174
	v_rcp_f32_e32 v211, v175
	v_rcp_f32_e32 v212, v182
	v_rcp_f32_e32 v213, v183
	v_pk_mul_f32 v[174:175], v[66:67], s[100:101] op_sel_hi:[1,0]
	v_pk_mul_f32 v[182:183], v[68:69], s[100:101] op_sel_hi:[1,0]
	v_exp_f32_e32 v174, v174
	v_exp_f32_e32 v175, v175
	v_exp_f32_e32 v182, v182
	v_exp_f32_e32 v183, v183
	v_pk_add_f32 v[174:175], v[174:175], 1.0 op_sel_hi:[1,0]
	v_pk_add_f32 v[182:183], v[182:183], 1.0 op_sel_hi:[1,0]
	v_rcp_f32_e32 v214, v174
	v_rcp_f32_e32 v215, v175
	v_rcp_f32_e32 v216, v182
	v_rcp_f32_e32 v217, v183
	s_waitcnt vmcnt(11)
; __device__ __forceinline__ float lo2f(unsigned w) { return __uint_as_float(w << 16); }
; __device__ __forceinline__ float hi2f(unsigned w) { return __uint_as_float(w & 0xffff0000u); }
; __device__ __forceinline__ float sigm(float x) { return __builtin_amdgcn_rcpf(1.f + __expf(-x)); }
;   __device__ __forceinline__ void operator()(const f32x4 (&acc)[2][2][4][2], const Unit& u, int wr, int wc, int fr, int fq) const {
;     ...
;       const int q = s - 4, bjq = q >> 1, nq = q & 1;
; #pragma unroll
;       for (int ai = 0; ai < 2; ++ai)
; #pragma unroll
;         for (int m = 0; m < 4; ++m) {
;           float o[4] = {0.f, 0.f, 0.f, 0.f};
; #pragma unroll
;           for (int bj = 0; bj < 2; ++bj)
; #pragma unroll
;             for (int n = 0; n < 2; ++n) {
;               const int ib = 2 * bj + n;
;               const uint2 b2 = *(reinterpret_cast<const uint2*>(brs + (size_t)(ib * 16 + (ai * 2 + bjq) * 4 + m) * 512 + tid) + nq);
;               const f32x4 g = acc[ai][bj][m][n];
;               o[0] += sigm(g[0]) * lo2f(b2.x); o[1] += sigm(g[1]) * hi2f(b2.x);
;               o[2] += sigm(g[2]) * lo2f(b2.y); o[3] += sigm(g[3]) * hi2f(b2.y);
;             }
;           const int r = u.pm * 256 + ai * 128 + wr * 64 + m * 16 + fr;
;           const int d = dq * 256 + 64 * q + 16 * wc + 4 * fq;
;           uint2 w; w.x = pack2(o[0], o[1]); w.y = pack2(o[2], o[3]);
;           *reinterpret_cast<uint2*>(ACC + (size_t)r * 1024 + d) = w;
;         }
	v_lshlrev_b32_e32 v218, 16, v146
	v_and_b32_e32 v219, 0xffff0000, v146
	v_lshlrev_b32_e32 v220, 16, v147
	v_and_b32_e32 v221, 0xffff0000, v147
	v_pk_fma_f32 v[222:223], v[202:203], v[218:219], 0 op_sel_hi:[1,1,0]
	v_pk_fma_f32 v[224:225], v[204:205], v[220:221], 0 op_sel_hi:[1,1,0]
	v_lshlrev_b32_e32 v218, 16, v148
	v_and_b32_e32 v219, 0xffff0000, v148
	v_lshlrev_b32_e32 v220, 16, v149
	v_and_b32_e32 v221, 0xffff0000, v149
	v_pk_fma_f32 v[222:223], v[206:207], v[218:219], v[222:223]
	v_pk_fma_f32 v[224:225], v[208:209], v[220:221], v[224:225]
	v_lshlrev_b32_e32 v218, 16, v150
	v_and_b32_e32 v219, 0xffff0000, v150
	v_lshlrev_b32_e32 v220, 16, v151
	v_and_b32_e32 v221, 0xffff0000, v151
	v_pk_fma_f32 v[222:223], v[210:211], v[218:219], v[222:223]
	v_pk_fma_f32 v[224:225], v[212:213], v[220:221], v[224:225]
	v_lshlrev_b32_e32 v218, 16, v152
	v_and_b32_e32 v219, 0xffff0000, v152
	v_lshlrev_b32_e32 v220, 16, v153
	v_and_b32_e32 v221, 0xffff0000, v153
	v_pk_fma_f32 v[222:223], v[214:215], v[218:219], v[222:223]
	v_pk_fma_f32 v[224:225], v[216:217], v[220:221], v[224:225]
	v_add_u32_e32 v170, 0x14000, v144
	global_load_dwordx2 v[146:147], v170, s[48:49]
	v_add_u32_e32 v171, 0x34000, v144
	global_load_dwordx2 v[148:149], v171, s[48:49]
	v_add_u32_e32 v172, 0x54000, v144
	global_load_dwordx2 v[150:151], v172, s[48:49]
	v_add_u32_e32 v173, 0x74000, v144
	global_load_dwordx2 v[152:153], v173, s[48:49]
	v_add_u32_e32 v231, 0x18000, v145
	v_cvt_pk_bf16_f32 v228, v222, v223
	v_cvt_pk_bf16_f32 v229, v224, v225
	global_store_dwordx2 v231, v[228:229], s[84:85]
	v_pk_mul_f32 v[174:175], v[62:63], s[100:101] op_sel_hi:[1,0]
	v_pk_mul_f32 v[182:183], v[64:65], s[100:101] op_sel_hi:[1,0]
	v_exp_f32_e32 v174, v174
	v_exp_f32_e32 v175, v175
	v_exp_f32_e32 v182, v182
	v_exp_f32_e32 v183, v183
	v_pk_add_f32 v[174:175], v[174:175], 1.0 op_sel_hi:[1,0]
	v_pk_add_f32 v[182:183], v[182:183], 1.0 op_sel_hi:[1,0]
	v_rcp_f32_e32 v202, v174
	v_rcp_f32_e32 v203, v175
	v_rcp_f32_e32 v204, v182
	v_rcp_f32_e32 v205, v183
	v_pk_mul_f32 v[174:175], v[58:59], s[100:101] op_sel_hi:[1,0]
	v_pk_mul_f32 v[182:183], v[60:61], s[100:101] op_sel_hi:[1,0]
	v_exp_f32_e32 v174, v174
	v_exp_f32_e32 v175, v175
	v_exp_f32_e32 v182, v182
	v_exp_f32_e32 v183, v183
	v_pk_add_f32 v[174:175], v[174:175], 1.0 op_sel_hi:[1,0]
	v_pk_add_f32 v[182:183], v[182:183], 1.0 op_sel_hi:[1,0]
	v_rcp_f32_e32 v206, v174
	v_rcp_f32_e32 v207, v175
	v_rcp_f32_e32 v208, v182
	v_rcp_f32_e32 v209, v183
	v_pk_mul_f32 v[174:175], v[30:31], s[100:101] op_sel_hi:[1,0]
	v_pk_mul_f32 v[182:183], v[32:33], s[100:101] op_sel_hi:[1,0]
	v_exp_f32_e32 v174, v174
	v_exp_f32_e32 v175, v175
	v_exp_f32_e32 v182, v182
	v_exp_f32_e32 v183, v183
	v_pk_add_f32 v[174:175], v[174:175], 1.0 op_sel_hi:[1,0]
	v_pk_add_f32 v[182:183], v[182:183], 1.0 op_sel_hi:[1,0]
	v_rcp_f32_e32 v210, v174
	v_rcp_f32_e32 v211, v175
	v_rcp_f32_e32 v212, v182
	v_rcp_f32_e32 v213, v183
	v_pk_mul_f32 v[174:175], v[26:27], s[100:101] op_sel_hi:[1,0]
	v_pk_mul_f32 v[182:183], v[28:29], s[100:101] op_sel_hi:[1,0]
	v_exp_f32_e32 v174, v174
	v_exp_f32_e32 v175, v175
	v_exp_f32_e32 v182, v182
	v_exp_f32_e32 v183, v183
	v_pk_add_f32 v[174:175], v[174:175], 1.0 op_sel_hi:[1,0]
	v_pk_add_f32 v[182:183], v[182:183], 1.0 op_sel_hi:[1,0]
	v_rcp_f32_e32 v214, v174
	v_rcp_f32_e32 v215, v175
	v_rcp_f32_e32 v216, v182
	v_rcp_f32_e32 v217, v183
	s_waitcnt vmcnt(11)
	v_lshlrev_b32_e32 v218, 16, v154
	v_and_b32_e32 v219, 0xffff0000, v154
	v_lshlrev_b32_e32 v220, 16, v155
	v_and_b32_e32 v221, 0xffff0000, v155
	v_pk_fma_f32 v[222:223], v[202:203], v[218:219], 0 op_sel_hi:[1,1,0]
	v_pk_fma_f32 v[224:225], v[204:205], v[220:221], 0 op_sel_hi:[1,1,0]
	v_lshlrev_b32_e32 v218, 16, v156
	v_and_b32_e32 v219, 0xffff0000, v156
	v_lshlrev_b32_e32 v220, 16, v157
	v_and_b32_e32 v221, 0xffff0000, v157
	v_pk_fma_f32 v[222:223], v[206:207], v[218:219], v[222:223]
	v_pk_fma_f32 v[224:225], v[208:209], v[220:221], v[224:225]
	v_lshlrev_b32_e32 v218, 16, v158
	v_and_b32_e32 v219, 0xffff0000, v158
	v_lshlrev_b32_e32 v220, 16, v159
	v_and_b32_e32 v221, 0xffff0000, v159
	v_pk_fma_f32 v[222:223], v[210:211], v[218:219], v[222:223]
	v_pk_fma_f32 v[224:225], v[212:213], v[220:221], v[224:225]
	v_lshlrev_b32_e32 v218, 16, v160
	v_and_b32_e32 v219, 0xffff0000, v160
	v_lshlrev_b32_e32 v220, 16, v161
	v_and_b32_e32 v221, 0xffff0000, v161
	v_pk_fma_f32 v[222:223], v[214:215], v[218:219], v[222:223]
	v_pk_fma_f32 v[224:225], v[216:217], v[220:221], v[224:225]
	v_add_u32_e32 v170, 0x16000, v144
	global_load_dwordx2 v[154:155], v170, s[48:49]
	v_add_u32_e32 v171, 0x36000, v144
	global_load_dwordx2 v[156:157], v171, s[48:49]
	v_add_u32_e32 v172, 0x56000, v144
	global_load_dwordx2 v[158:159], v172, s[48:49]
	v_add_u32_e32 v173, 0x76000, v144
	global_load_dwordx2 v[160:161], v173, s[48:49]
	v_add_u32_e32 v230, 0x40000, v145
	v_cvt_pk_bf16_f32 v226, v222, v223
	v_cvt_pk_bf16_f32 v227, v224, v225
	global_store_dwordx2 v230, v[226:227], s[84:85]
	v_pk_mul_f32 v[174:175], v[54:55], s[100:101] op_sel_hi:[1,0]
	v_pk_mul_f32 v[182:183], v[56:57], s[100:101] op_sel_hi:[1,0]
	v_exp_f32_e32 v174, v174
	v_exp_f32_e32 v175, v175
	v_exp_f32_e32 v182, v182
	v_exp_f32_e32 v183, v183
	v_pk_add_f32 v[174:175], v[174:175], 1.0 op_sel_hi:[1,0]
	v_pk_add_f32 v[182:183], v[182:183], 1.0 op_sel_hi:[1,0]
	v_rcp_f32_e32 v202, v174
	v_rcp_f32_e32 v203, v175
	v_rcp_f32_e32 v204, v182
	v_rcp_f32_e32 v205, v183
	v_pk_mul_f32 v[174:175], v[50:51], s[100:101] op_sel_hi:[1,0]
	v_pk_mul_f32 v[182:183], v[52:53], s[100:101] op_sel_hi:[1,0]
	v_exp_f32_e32 v174, v174
	v_exp_f32_e32 v175, v175
	v_exp_f32_e32 v182, v182
	v_exp_f32_e32 v183, v183
	v_pk_add_f32 v[174:175], v[174:175], 1.0 op_sel_hi:[1,0]
	v_pk_add_f32 v[182:183], v[182:183], 1.0 op_sel_hi:[1,0]
	v_rcp_f32_e32 v206, v174
	v_rcp_f32_e32 v207, v175
	v_rcp_f32_e32 v208, v182
	v_rcp_f32_e32 v209, v183
	v_pk_mul_f32 v[174:175], v[22:23], s[100:101] op_sel_hi:[1,0]
	v_pk_mul_f32 v[182:183], v[24:25], s[100:101] op_sel_hi:[1,0]
	v_exp_f32_e32 v174, v174
	v_exp_f32_e32 v175, v175
	v_exp_f32_e32 v182, v182
	v_exp_f32_e32 v183, v183
	v_pk_add_f32 v[174:175], v[174:175], 1.0 op_sel_hi:[1,0]
	v_pk_add_f32 v[182:183], v[182:183], 1.0 op_sel_hi:[1,0]
	v_rcp_f32_e32 v210, v174
	v_rcp_f32_e32 v211, v175
	v_rcp_f32_e32 v212, v182
	v_rcp_f32_e32 v213, v183
	v_pk_mul_f32 v[174:175], v[18:19], s[100:101] op_sel_hi:[1,0]
	v_pk_mul_f32 v[182:183], v[20:21], s[100:101] op_sel_hi:[1,0]
	v_exp_f32_e32 v174, v174
	v_exp_f32_e32 v175, v175
	v_exp_f32_e32 v182, v182
	v_exp_f32_e32 v183, v183
	v_pk_add_f32 v[174:175], v[174:175], 1.0 op_sel_hi:[1,0]
	v_pk_add_f32 v[182:183], v[182:183], 1.0 op_sel_hi:[1,0]
	v_rcp_f32_e32 v214, v174
	v_rcp_f32_e32 v215, v175
	v_rcp_f32_e32 v216, v182
	v_rcp_f32_e32 v217, v183
	s_waitcnt vmcnt(11)
; __device__ __forceinline__ float lo2f(unsigned w) { return __uint_as_float(w << 16); }
; __device__ __forceinline__ float hi2f(unsigned w) { return __uint_as_float(w & 0xffff0000u); }
; __device__ __forceinline__ float sigm(float x) { return __builtin_amdgcn_rcpf(1.f + __expf(-x)); }
;   __device__ __forceinline__ void operator()(const f32x4 (&acc)[2][2][4][2], const Unit& u, int wr, int wc, int fr, int fq) const {
;     ...
;       const int q = s - 4, bjq = q >> 1, nq = q & 1;
; #pragma unroll
;       for (int ai = 0; ai < 2; ++ai)
; #pragma unroll
;         for (int m = 0; m < 4; ++m) {
;           float o[4] = {0.f, 0.f, 0.f, 0.f};
; #pragma unroll
;           for (int bj = 0; bj < 2; ++bj)
; #pragma unroll
;             for (int n = 0; n < 2; ++n) {
;               const int ib = 2 * bj + n;
;               const uint2 b2 = *(reinterpret_cast<const uint2*>(brs + (size_t)(ib * 16 + (ai * 2 + bjq) * 4 + m) * 512 + tid) + nq);
;               const f32x4 g = acc[ai][bj][m][n];
;               o[0] += sigm(g[0]) * lo2f(b2.x); o[1] += sigm(g[1]) * hi2f(b2.x);
;               o[2] += sigm(g[2]) * lo2f(b2.y); o[3] += sigm(g[3]) * hi2f(b2.y);
;             }
;           const int r = u.pm * 256 + ai * 128 + wr * 64 + m * 16 + fr;
;           const int d = dq * 256 + 64 * q + 16 * wc + 4 * fq;
;           uint2 w; w.x = pack2(o[0], o[1]); w.y = pack2(o[2], o[3]);
;           *reinterpret_cast<uint2*>(ACC + (size_t)r * 1024 + d) = w;
;         }
	v_lshlrev_b32_e32 v218, 16, v162
	v_and_b32_e32 v219, 0xffff0000, v162
	v_lshlrev_b32_e32 v220, 16, v163
	v_and_b32_e32 v221, 0xffff0000, v163
	v_pk_fma_f32 v[222:223], v[202:203], v[218:219], 0 op_sel_hi:[1,1,0]
	v_pk_fma_f32 v[224:225], v[204:205], v[220:221], 0 op_sel_hi:[1,1,0]
	v_lshlrev_b32_e32 v218, 16, v164
	v_and_b32_e32 v219, 0xffff0000, v164
	v_lshlrev_b32_e32 v220, 16, v165
	v_and_b32_e32 v221, 0xffff0000, v165
	v_pk_fma_f32 v[222:223], v[206:207], v[218:219], v[222:223]
	v_pk_fma_f32 v[224:225], v[208:209], v[220:221], v[224:225]
	v_lshlrev_b32_e32 v218, 16, v166
	v_and_b32_e32 v219, 0xffff0000, v166
	v_lshlrev_b32_e32 v220, 16, v167
	v_and_b32_e32 v221, 0xffff0000, v167
	v_pk_fma_f32 v[222:223], v[210:211], v[218:219], v[222:223]
	v_pk_fma_f32 v[224:225], v[212:213], v[220:221], v[224:225]
	v_lshlrev_b32_e32 v218, 16, v168
	v_and_b32_e32 v219, 0xffff0000, v168
	v_lshlrev_b32_e32 v220, 16, v169
	v_and_b32_e32 v221, 0xffff0000, v169
	v_pk_fma_f32 v[222:223], v[214:215], v[218:219], v[222:223]
	v_pk_fma_f32 v[224:225], v[216:217], v[220:221], v[224:225]
	v_add_u32_e32 v231, 0x48000, v145
	v_cvt_pk_bf16_f32 v228, v222, v223
	v_cvt_pk_bf16_f32 v229, v224, v225
	global_store_dwordx2 v231, v[228:229], s[84:85]
	v_pk_mul_f32 v[174:175], v[46:47], s[100:101] op_sel_hi:[1,0]
	v_pk_mul_f32 v[182:183], v[48:49], s[100:101] op_sel_hi:[1,0]
	v_exp_f32_e32 v174, v174
	v_exp_f32_e32 v175, v175
	v_exp_f32_e32 v182, v182
	v_exp_f32_e32 v183, v183
	v_pk_add_f32 v[174:175], v[174:175], 1.0 op_sel_hi:[1,0]
	v_pk_add_f32 v[182:183], v[182:183], 1.0 op_sel_hi:[1,0]
	v_rcp_f32_e32 v202, v174
	v_rcp_f32_e32 v203, v175
	v_rcp_f32_e32 v204, v182
	v_rcp_f32_e32 v205, v183
	v_pk_mul_f32 v[174:175], v[42:43], s[100:101] op_sel_hi:[1,0]
	v_pk_mul_f32 v[182:183], v[44:45], s[100:101] op_sel_hi:[1,0]
	v_exp_f32_e32 v174, v174
	v_exp_f32_e32 v175, v175
	v_exp_f32_e32 v182, v182
	v_exp_f32_e32 v183, v183
	v_pk_add_f32 v[174:175], v[174:175], 1.0 op_sel_hi:[1,0]
	v_pk_add_f32 v[182:183], v[182:183], 1.0 op_sel_hi:[1,0]
	v_rcp_f32_e32 v206, v174
	v_rcp_f32_e32 v207, v175
	v_rcp_f32_e32 v208, v182
	v_rcp_f32_e32 v209, v183
	v_pk_mul_f32 v[174:175], v[14:15], s[100:101] op_sel_hi:[1,0]
	v_pk_mul_f32 v[182:183], v[16:17], s[100:101] op_sel_hi:[1,0]
	v_exp_f32_e32 v174, v174
	v_exp_f32_e32 v175, v175
	v_exp_f32_e32 v182, v182
	v_exp_f32_e32 v183, v183
	v_pk_add_f32 v[174:175], v[174:175], 1.0 op_sel_hi:[1,0]
	v_pk_add_f32 v[182:183], v[182:183], 1.0 op_sel_hi:[1,0]
	v_rcp_f32_e32 v210, v174
	v_rcp_f32_e32 v211, v175
	v_rcp_f32_e32 v212, v182
	v_rcp_f32_e32 v213, v183
	v_pk_mul_f32 v[174:175], v[10:11], s[100:101] op_sel_hi:[1,0]
	v_pk_mul_f32 v[182:183], v[12:13], s[100:101] op_sel_hi:[1,0]
	v_exp_f32_e32 v174, v174
	v_exp_f32_e32 v175, v175
	v_exp_f32_e32 v182, v182
	v_exp_f32_e32 v183, v183
	v_pk_add_f32 v[174:175], v[174:175], 1.0 op_sel_hi:[1,0]
	v_pk_add_f32 v[182:183], v[182:183], 1.0 op_sel_hi:[1,0]
	v_rcp_f32_e32 v214, v174
	v_rcp_f32_e32 v215, v175
	v_rcp_f32_e32 v216, v182
	v_rcp_f32_e32 v217, v183
	s_waitcnt vmcnt(7)
; __device__ __forceinline__ float lo2f(unsigned w) { return __uint_as_float(w << 16); }
; __device__ __forceinline__ float hi2f(unsigned w) { return __uint_as_float(w & 0xffff0000u); }
; __device__ __forceinline__ float sigm(float x) { return __builtin_amdgcn_rcpf(1.f + __expf(-x)); }
;   __device__ __forceinline__ void operator()(const f32x4 (&acc)[2][2][4][2], const Unit& u, int wr, int wc, int fr, int fq) const {
;     ...
;       const int q = s - 4, bjq = q >> 1, nq = q & 1;
; #pragma unroll
;       for (int ai = 0; ai < 2; ++ai)
; #pragma unroll
;         for (int m = 0; m < 4; ++m) {
;           float o[4] = {0.f, 0.f, 0.f, 0.f};
; #pragma unroll
;           for (int bj = 0; bj < 2; ++bj)
; #pragma unroll
;             for (int n = 0; n < 2; ++n) {
;               const int ib = 2 * bj + n;
;               const uint2 b2 = *(reinterpret_cast<const uint2*>(brs + (size_t)(ib * 16 + (ai * 2 + bjq) * 4 + m) * 512 + tid) + nq);
;               const f32x4 g = acc[ai][bj][m][n];
;               o[0] += sigm(g[0]) * lo2f(b2.x); o[1] += sigm(g[1]) * hi2f(b2.x);
;               o[2] += sigm(g[2]) * lo2f(b2.y); o[3] += sigm(g[3]) * hi2f(b2.y);
;             }
;           const int r = u.pm * 256 + ai * 128 + wr * 64 + m * 16 + fr;
;           const int d = dq * 256 + 64 * q + 16 * wc + 4 * fq;
;           uint2 w; w.x = pack2(o[0], o[1]); w.y = pack2(o[2], o[3]);
;           *reinterpret_cast<uint2*>(ACC + (size_t)r * 1024 + d) = w;
;         }
	v_lshlrev_b32_e32 v218, 16, v146
	v_and_b32_e32 v219, 0xffff0000, v146
	v_lshlrev_b32_e32 v220, 16, v147
	v_and_b32_e32 v221, 0xffff0000, v147
	v_pk_fma_f32 v[222:223], v[202:203], v[218:219], 0 op_sel_hi:[1,1,0]
	v_pk_fma_f32 v[224:225], v[204:205], v[220:221], 0 op_sel_hi:[1,1,0]
	v_lshlrev_b32_e32 v218, 16, v148
	v_and_b32_e32 v219, 0xffff0000, v148
	v_lshlrev_b32_e32 v220, 16, v149
	v_and_b32_e32 v221, 0xffff0000, v149
	v_pk_fma_f32 v[222:223], v[206:207], v[218:219], v[222:223]
	v_pk_fma_f32 v[224:225], v[208:209], v[220:221], v[224:225]
	v_lshlrev_b32_e32 v218, 16, v150
	v_and_b32_e32 v219, 0xffff0000, v150
	v_lshlrev_b32_e32 v220, 16, v151
	v_and_b32_e32 v221, 0xffff0000, v151
	v_pk_fma_f32 v[222:223], v[210:211], v[218:219], v[222:223]
	v_pk_fma_f32 v[224:225], v[212:213], v[220:221], v[224:225]
	v_lshlrev_b32_e32 v218, 16, v152
	v_and_b32_e32 v219, 0xffff0000, v152
	v_lshlrev_b32_e32 v220, 16, v153
	v_and_b32_e32 v221, 0xffff0000, v153
	v_pk_fma_f32 v[222:223], v[214:215], v[218:219], v[222:223]
	v_pk_fma_f32 v[224:225], v[216:217], v[220:221], v[224:225]
	v_add_u32_e32 v230, 0x50000, v145
	v_cvt_pk_bf16_f32 v226, v222, v223
	v_cvt_pk_bf16_f32 v227, v224, v225
	global_store_dwordx2 v230, v[226:227], s[84:85]
	v_pk_mul_f32 v[174:175], v[38:39], s[100:101] op_sel_hi:[1,0]
	v_pk_mul_f32 v[182:183], v[40:41], s[100:101] op_sel_hi:[1,0]
	v_exp_f32_e32 v174, v174
	v_exp_f32_e32 v175, v175
	v_exp_f32_e32 v182, v182
	v_exp_f32_e32 v183, v183
	v_pk_add_f32 v[174:175], v[174:175], 1.0 op_sel_hi:[1,0]
	v_pk_add_f32 v[182:183], v[182:183], 1.0 op_sel_hi:[1,0]
	v_rcp_f32_e32 v202, v174
	v_rcp_f32_e32 v203, v175
	v_rcp_f32_e32 v204, v182
	v_rcp_f32_e32 v205, v183
	v_pk_mul_f32 v[174:175], v[34:35], s[100:101] op_sel_hi:[1,0]
	v_pk_mul_f32 v[182:183], v[36:37], s[100:101] op_sel_hi:[1,0]
	v_exp_f32_e32 v174, v174
	v_exp_f32_e32 v175, v175
	v_exp_f32_e32 v182, v182
	v_exp_f32_e32 v183, v183
	v_pk_add_f32 v[174:175], v[174:175], 1.0 op_sel_hi:[1,0]
	v_pk_add_f32 v[182:183], v[182:183], 1.0 op_sel_hi:[1,0]
	v_rcp_f32_e32 v206, v174
	v_rcp_f32_e32 v207, v175
	v_rcp_f32_e32 v208, v182
	v_rcp_f32_e32 v209, v183
	v_pk_mul_f32 v[174:175], v[6:7], s[100:101] op_sel_hi:[1,0]
	v_pk_mul_f32 v[182:183], v[8:9], s[100:101] op_sel_hi:[1,0]
	v_exp_f32_e32 v174, v174
	v_exp_f32_e32 v175, v175
	v_exp_f32_e32 v182, v182
	v_exp_f32_e32 v183, v183
	v_pk_add_f32 v[174:175], v[174:175], 1.0 op_sel_hi:[1,0]
	v_pk_add_f32 v[182:183], v[182:183], 1.0 op_sel_hi:[1,0]
	v_rcp_f32_e32 v210, v174
	v_rcp_f32_e32 v211, v175
	v_rcp_f32_e32 v212, v182
	v_rcp_f32_e32 v213, v183
	v_pk_mul_f32 v[174:175], v[2:3], s[100:101] op_sel_hi:[1,0]
	v_pk_mul_f32 v[182:183], v[4:5], s[100:101] op_sel_hi:[1,0]
	v_exp_f32_e32 v174, v174
	v_exp_f32_e32 v175, v175
	v_exp_f32_e32 v182, v182
	v_exp_f32_e32 v183, v183
	v_pk_add_f32 v[174:175], v[174:175], 1.0 op_sel_hi:[1,0]
	v_pk_add_f32 v[182:183], v[182:183], 1.0 op_sel_hi:[1,0]
	v_rcp_f32_e32 v214, v174
	v_rcp_f32_e32 v215, v175
	v_rcp_f32_e32 v216, v182
	v_rcp_f32_e32 v217, v183
	s_waitcnt vmcnt(3)
	v_lshlrev_b32_e32 v218, 16, v154
	v_and_b32_e32 v219, 0xffff0000, v154
	v_lshlrev_b32_e32 v220, 16, v155
	v_and_b32_e32 v221, 0xffff0000, v155
	v_pk_fma_f32 v[222:223], v[202:203], v[218:219], 0 op_sel_hi:[1,1,0]
	v_pk_fma_f32 v[224:225], v[204:205], v[220:221], 0 op_sel_hi:[1,1,0]
	v_lshlrev_b32_e32 v218, 16, v156
	v_and_b32_e32 v219, 0xffff0000, v156
	v_lshlrev_b32_e32 v220, 16, v157
	v_and_b32_e32 v221, 0xffff0000, v157
	v_pk_fma_f32 v[222:223], v[206:207], v[218:219], v[222:223]
	v_pk_fma_f32 v[224:225], v[208:209], v[220:221], v[224:225]
	v_lshlrev_b32_e32 v218, 16, v158
	v_and_b32_e32 v219, 0xffff0000, v158
	v_lshlrev_b32_e32 v220, 16, v159
	v_and_b32_e32 v221, 0xffff0000, v159
	v_pk_fma_f32 v[222:223], v[210:211], v[218:219], v[222:223]
	v_pk_fma_f32 v[224:225], v[212:213], v[220:221], v[224:225]
	v_lshlrev_b32_e32 v218, 16, v160
	v_and_b32_e32 v219, 0xffff0000, v160
	v_lshlrev_b32_e32 v220, 16, v161
	v_and_b32_e32 v221, 0xffff0000, v161
	v_pk_fma_f32 v[222:223], v[214:215], v[218:219], v[222:223]
	v_pk_fma_f32 v[224:225], v[216:217], v[220:221], v[224:225]
	v_add_u32_e32 v231, 0x58000, v145
	v_cvt_pk_bf16_f32 v228, v222, v223
	v_cvt_pk_bf16_f32 v229, v224, v225
	global_store_dwordx2 v231, v[228:229], s[84:85]
	s_cbranch_execnz .LBB0_1415
